# strategy 4: static s_setprio 1 for waves 4-7 (younger half) during the chunk-prep loop
# speedup vs baseline: 1.0132x; 1.0070x over previous
.LBB0_268:
	v_mov_b32_e32 v141, 0
	v_lshlrev_b32_e32 v140, 4, v94
	v_lshl_add_u64 v[98:99], s[70:71], 0, v[140:141]
	s_mov_b64 s[6:7], 0x7600000
	v_lshl_add_u32 v133, v1, 15, 0
	v_lshlrev_b32_e32 v96, 2, v131
	v_lshl_add_u64 v[142:143], v[98:99], 0, s[6:7]
	s_mov_b64 s[6:7], 0x7630000
	v_add_u32_e32 v135, v133, v96
	v_lshlrev_b32_e32 v136, 4, v95
	v_lshl_add_u64 v[144:145], v[98:99], 0, s[6:7]
	s_mov_b64 s[6:7], 0x7660000
	v_sub_u32_e32 v97, v135, v136
	v_lshl_add_u64 v[146:147], v[98:99], 0, s[6:7]
	v_mul_u32_u24_e32 v98, 0x48, v134
	v_lshl_add_u32 v165, v98, 1, v97
	v_mov_b32_e32 v97, v141
	v_bfe_u32 v100, v0, 6, 1
	v_lshl_add_u64 v[96:97], s[70:71], 0, v[96:97]
	s_mov_b64 s[14:15], 0x15a08000
	v_add_u32_e32 v101, 0x1b00, v133
	v_cmp_gt_u32_e64 s[8:9], 64, v4
	v_lshl_add_u32 v161, v4, 2, v133
	v_cmp_gt_u32_e64 s[10:11], 8, v4
	v_lshl_add_u64 v[154:155], v[96:97], 0, s[14:15]
	v_and_b32_e32 v4, 64, v0
	v_cmp_eq_u32_e32 vcc, 0, v100
	v_mul_u32_u24_e32 v96, 0x48, v132
	v_lshl_or_b32 v149, v100, 5, v132
	v_lshl_add_u64 v[156:157], s[12:13], 0, v[140:141]
	v_cmp_ne_u32_e64 s[12:13], 0, v4
	v_cndmask_b32_e32 v4, v101, v133, vcc
	v_lshlrev_b32_e32 v99, 1, v96
	v_lshlrev_b32_e32 v96, 1, v132
	v_mov_b32_e32 v97, v141
	v_lshlrev_b32_e32 v148, 2, v94
	v_add3_u32 v167, v4, v99, v140
	v_add_u32_e32 v101, v133, v96
	v_lshl_add_u64 v[158:159], s[68:69], 0, v[96:97]
	v_cmp_gt_u32_e64 s[14:15], 32, v3
	v_add_u32_e32 v97, v133, v140
	v_lshrrev_b32_e32 v160, 2, v3
	v_lshlrev_b32_e32 v140, 1, v3
	v_lshlrev_b32_e32 v3, 2, v149
	v_add_u32_e32 v102, v101, v96
	v_lshl_or_b32 v96, v94, 10, v3
	v_or_b32_e32 v164, 1, v148
	v_add_u32_e32 v169, v133, v96
	v_lshl_or_b32 v96, v164, 8, v3
	v_or_b32_e32 v166, 2, v148
	v_add_u32_e32 v171, v133, v96
	v_lshl_or_b32 v96, v166, 8, v3
	v_cmp_lt_u32_e64 s[20:21], v132, v166
	v_add_u32_e32 v194, v133, v96
	v_or_b32_e32 v168, 3, v148
	v_cndmask_b32_e64 v96, 0, 1, s[20:21]
	v_cmp_le_u32_e64 s[20:21], v132, v166
	s_add_u32 s30, s70, 0x7900000
	v_lshl_or_b32 v3, v168, 8, v3
	v_add_u32_e32 v199, v97, v99
	v_cndmask_b32_e64 v99, 0, 1, s[20:21]
	s_addc_u32 s31, s71, 0
	v_add_u32_e32 v195, v133, v3
	v_mul_u32_u24_e32 v3, 0xc0, v95
	v_cndmask_b32_e32 v96, v99, v96, vcc
	s_add_u32 s42, s70, 0x9900000
	v_lshlrev_b32_e32 v150, 1, v134
	v_lshlrev_b32_e32 v3, 1, v3
	v_cmp_lt_u32_e64 s[16:17], v132, v148
	v_and_b32_e32 v96, 1, v96
	v_cmp_lt_u32_e64 s[22:23], v132, v168
	s_addc_u32 s43, s71, 0
	s_waitcnt lgkmcnt(0)
	s_load_dword s3, s[0:1], 0xd8
	v_add3_u32 v197, v133, v150, v3
	v_add3_u32 v198, v133, v3, v150
	v_cndmask_b32_e64 v3, 0, 1, s[16:17]
	v_cmp_le_u32_e64 s[16:17], v132, v148
	v_cmp_eq_u32_e64 s[20:21], 1, v96
	v_cndmask_b32_e64 v96, 0, 1, s[22:23]
	v_cmp_le_u32_e64 s[22:23], v132, v168
	s_add_u32 s46, s70, 0x15c08000
	v_cmp_eq_u32_e64 s[6:7], 0, v95
	v_lshlrev_b32_e32 v152, 1, v95
	v_cndmask_b32_e64 v95, 0, 1, s[16:17]
	v_cndmask_b32_e64 v99, 0, 1, s[22:23]
	s_addc_u32 s47, s71, 0
	s_movk_i32 s24, 0x210
	v_cndmask_b32_e32 v3, v95, v3, vcc
	v_cndmask_b32_e32 v96, v99, v96, vcc
	s_add_u32 s50, s70, 0xb900000
	v_and_b32_e32 v3, 1, v3
	v_and_b32_e32 v96, 1, v96
	s_movk_i32 s25, 0x840
	v_mad_u32_u24 v108, v164, s24, v133
	s_addc_u32 s51, s71, 0
	v_cmp_eq_u32_e64 s[16:17], 1, v3
	v_mul_u32_u24_e32 v3, 0x110, v94
	v_or_b32_e32 v95, v148, v100
	v_cmp_eq_u32_e64 s[22:23], 1, v96
	v_lshl_or_b32 v99, v100, 1, 1
	v_lshlrev_b32_e32 v96, 4, v100
	v_mul_u32_u24_e32 v104, 0xc0, v94
	v_lshlrev_b32_e32 v100, 7, v100
	v_mad_u32_u24 v94, v94, s25, v133
	v_lshlrev_b32_e32 v107, 2, v132
	v_add_u32_e32 v109, 0x210, v108
	v_add_u32_e32 v110, 0x420, v108
	s_waitcnt lgkmcnt(0)
	s_cmpk_lg_i32 s3, 0x100
	v_lshlrev_b32_e32 v4, 4, v0
	v_add3_u32 v200, v94, v100, v107
	v_add3_u32 v201, v108, v100, v107
	v_add3_u32 v202, v109, v100, v107
	v_add3_u32 v203, v110, v100, v107
	v_lshl_or_b32 v100, v99, 4, v132
	s_cselect_b64 s[52:53], -1, 0
	v_mul_u32_u24_e32 v98, 0x210, v134
	v_mul_u32_u24_e32 v103, 48, v132
	v_and_b32_e32 v4, 48, v4
	v_cmp_gt_u32_e64 s[18:19], v132, v95
	v_mul_u32_u24_e32 v95, 0x44, v164
	v_mul_u32_u24_e32 v105, 48, v164
	v_mul_u32_u24_e32 v106, 48, v149
	v_mul_u32_u24_e32 v100, 48, v100
	v_lshlrev_b32_e32 v99, 6, v99
	s_lshl_b32 s64, s3, 2
	v_lshl_add_u32 v153, v134, 8, v135
	v_mov_b32_e32 v137, v141
	v_mov_b32_e32 v151, v141
	v_lshl_add_u64 v[162:163], s[30:31], 0, v[140:141]
	v_or_b32_e32 v196, 16, v149
	v_or_b32_e32 v170, 1, v152
	v_add3_u32 v204, v94, v99, v107
	v_add3_u32 v205, v108, v99, v107
	v_add3_u32 v206, v109, v99, v107
	v_add3_u32 v207, v110, v99, v107
	s_lshl_b32 s65, s2, 2
	v_or_b32_e32 v208, s64, v1
	s_movk_i32 s66, 0xff0
	s_mov_b32 s67, 0xbfb8aa3b
	s_mov_b32 s74, 0x800000
	s_mov_b32 s75, 0x3f317217
	s_mov_b32 s76, 0x7f800000
	s_mov_b32 s77, 0xf800000
	v_mov_b32_e32 v209, 0x260
	v_add_u32_e32 v210, v135, v98
	s_movk_i32 s78, 0x3c0
	s_movk_i32 s79, 0x1800
	s_movk_i32 s80, 0x1000
	v_add_u32_e32 v211, v102, v3
	v_lshlrev_b32_e32 v172, 1, v96
	v_add_u32_e32 v212, v101, v104
	v_add_u32_e32 v213, v97, v106
	v_add_u32_e32 v214, v97, v100
	v_lshlrev_b32_e32 v174, 1, v4
	v_mov_b32_e32 v215, 0x41b17218
	v_add_u32_e32 v216, v102, v95
	v_add_u32_e32 v217, v101, v105
	v_add_u32_e32 v218, v97, v103
	s_mov_b32 s81, s2
	v_readfirstlane_b32 vcc_lo, v0
	s_nop 1
	s_lshr_b32 vcc_lo, vcc_lo, 6
	s_cmp_lt_u32 vcc_lo, 4
	s_cbranch_scc1 .Lprep_in
	s_setprio 1
	s_barrier
	s_barrier
	s_barrier

.Lprep_out:
	s_setprio 0
	v_readfirstlane_b32 vcc_lo, v0
	s_nop 1
	s_lshr_b32 vcc_lo, vcc_lo, 6
	s_cmp_gt_u32 vcc_lo, 3
	s_cbranch_scc1 .LBB0_326
	s_barrier
	s_barrier
	s_barrier

.Lat_pv_done:
	s_nop 7
	v_cvt_pk_bf16_f32 v22, v240, v240
	v_cvt_pk_bf16_f32 v23, v241, v241
	v_cvt_pk_bf16_f32 v24, v242, v242
	v_cvt_pk_bf16_f32 v25, v243, v243
	v_cvt_pk_bf16_f32 v26, v244, v244
	v_cvt_pk_bf16_f32 v27, v245, v245
	v_cvt_pk_bf16_f32 v28, v246, v246
	v_cvt_pk_bf16_f32 v29, v247, v247
	v_cvt_pk_bf16_f32 v134, v248, v248
	v_cvt_pk_bf16_f32 v135, v249, v249
	v_cvt_pk_bf16_f32 v136, v250, v250
	v_cvt_pk_bf16_f32 v137, v251, v251
	v_cvt_pk_bf16_f32 v138, v120, v120
	v_cvt_pk_bf16_f32 v139, v121, v121
	v_cvt_pk_bf16_f32 v150, v122, v122
	v_cvt_pk_bf16_f32 v151, v123, v123
	global_store_short v17, v22, s[20:21]
	global_store_short v17, v23, s[20:21] offset:2048
	global_store_short v18, v24, s[20:21]
	global_store_short v18, v25, s[20:21] offset:2048
	global_store_short v17, v26, s[20:21] offset:32
	global_store_short v17, v27, s[20:21] offset:2080
	global_store_short v18, v28, s[20:21] offset:32
	global_store_short v18, v29, s[20:21] offset:2080
	global_store_short v17, v134, s[20:21] offset:64
	global_store_short v17, v135, s[20:21] offset:2112
	global_store_short v18, v136, s[20:21] offset:64
	global_store_short v18, v137, s[20:21] offset:2112
	global_store_short v17, v138, s[20:21] offset:96
	global_store_short v17, v139, s[20:21] offset:2144
	global_store_short v18, v150, s[20:21] offset:96
	global_store_short v18, v151, s[20:21] offset:2144
	s_add_u32 s3, s3, s6
	s_cmp_lt_u32 s3, 0x2000
	s_cbranch_scc1 .Lat_loop
	v_and_b32_e32 v10, 15, v0
	s_add_u32 s74, s0, 0xd8
	s_addc_u32 s75, s1, 0
	v_mov_b64_e32 v[2:3], s[74:75]
	s_mov_b64 s[64:65], exec
	s_nop 0
	s_nop 0
	s_nop 0
	s_nop 0
	s_nop 0
	s_nop 0
	s_nop 0
	s_nop 0
	s_nop 0
	s_nop 0
	s_nop 0
	s_nop 0
	s_nop 0
	s_nop 0
	s_nop 0
